# wt3_pz + G1/G3: the unit's row-statistics lines are touched (1 dword load per wave) one K iteration before the epilogue so its loads hit L2
# baseline (speedup 1.0000x reference)
.LBB0_322:
	s_add_u32 s4, s0, 0xfffc0080
	s_addc_u32 s5, s1, -1
	s_add_i32 s44, 0, 0x10000
	s_cmp_eq_u32 s93, 12
	s_cselect_b32 s71, s31, s5
	s_cselect_b32 s70, s39, s4
	s_cselect_b32 s69, s41, s92
	s_cselect_b32 s68, s40, s91
	s_add_i32 s4, 0, 0x14000
	v_add_u32_e32 v144, s44, v175
	v_add_u32_e32 v168, s4, v175
	ds_read_b128 v[132:135], v144
	ds_read_b128 v[136:139], v144 offset:1024
	ds_read_b128 v[140:143], v144 offset:2048
	ds_read_b128 v[144:147], v144 offset:3072
	ds_read_b128 v[156:159], v168
	ds_read_b128 v[160:163], v168 offset:1024
	ds_read_b128 v[164:167], v168 offset:2048
	ds_read_b128 v[180:183], v168 offset:3072
	s_add_i32 s94, s77, 0
	v_lshl_add_u64 v[168:169], s[0:1], 0, v[98:99]
	s_add_i32 m0, s94, 0xc000
	ds_read_b128 v[184:187], v179
	ds_read_b128 v[188:191], v179 offset:1024
	ds_read_b128 v[192:195], v179 offset:2048
	ds_read_b128 v[204:207], v179 offset:3072
	ds_read_b128 v[208:211], v179 offset:4096
	ds_read_b128 v[212:215], v179 offset:5120
	ds_read_b128 v[216:219], v179 offset:6144
	ds_read_b128 v[220:223], v179 offset:7168
	global_load_lds_dwordx4 v[168:169], off
	v_lshl_add_u64 v[168:169], s[0:1], 0, v[150:151]
	s_add_i32 m0, s94, 0xe000
	s_nop 0
	global_load_lds_dwordx4 v[168:169], off
	s_cmp_eq_u32 s93, 12
	s_cbranch_scc1 .Lmy_w9_g1_1
	s_waitcnt vmcnt(8)
	s_branch .Lmy_w9d_g1_1

.Lmy_w9d_g1_1:
	s_waitcnt lgkmcnt(0)
	s_setprio 1
	s_barrier
	v_mfma_f32_16x16x32_bf16 v[128:131], v[132:135], v[184:187], v[128:131]
	v_mfma_f32_16x16x32_bf16 v[124:127], v[140:143], v[184:187], v[124:127]
	v_mfma_f32_16x16x32_bf16 v[120:123], v[132:135], v[192:195], v[120:123]
	v_mfma_f32_16x16x32_bf16 v[112:115], v[140:143], v[192:195], v[112:115]
	v_mfma_f32_16x16x32_bf16 v[104:107], v[132:135], v[208:211], v[104:107]
	v_mfma_f32_16x16x32_bf16 v[94:97], v[140:143], v[208:211], v[94:97]
	v_mfma_f32_16x16x32_bf16 v[86:89], v[132:135], v[216:219], v[86:89]
	v_mfma_f32_16x16x32_bf16 v[78:81], v[140:143], v[216:219], v[78:81]
	v_mfma_f32_16x16x32_bf16 v[128:131], v[136:139], v[188:191], v[128:131]
	v_mfma_f32_16x16x32_bf16 v[124:127], v[144:147], v[188:191], v[124:127]
	v_mfma_f32_16x16x32_bf16 v[120:123], v[136:139], v[204:207], v[120:123]
	v_mfma_f32_16x16x32_bf16 v[112:115], v[144:147], v[204:207], v[112:115]
	v_mfma_f32_16x16x32_bf16 v[104:107], v[136:139], v[212:215], v[104:107]
	v_mfma_f32_16x16x32_bf16 v[94:97], v[144:147], v[212:215], v[94:97]
	v_mfma_f32_16x16x32_bf16 v[86:89], v[136:139], v[220:223], v[86:89]
	v_mfma_f32_16x16x32_bf16 v[78:81], v[144:147], v[220:223], v[78:81]
	s_setprio 0
	s_setprio 1
	v_mfma_f32_16x16x32_bf16 v[116:119], v[156:159], v[184:187], v[116:119]
	v_mfma_f32_16x16x32_bf16 v[108:111], v[164:167], v[184:187], v[108:111]
	v_mfma_f32_16x16x32_bf16 v[100:103], v[156:159], v[192:195], v[100:103]
	v_mfma_f32_16x16x32_bf16 v[90:93], v[164:167], v[192:195], v[90:93]
	v_mfma_f32_16x16x32_bf16 v[82:85], v[156:159], v[208:211], v[82:85]
	v_mfma_f32_16x16x32_bf16 v[74:77], v[164:167], v[208:211], v[74:77]
	v_mfma_f32_16x16x32_bf16 v[70:73], v[156:159], v[216:219], v[70:73]
	v_mfma_f32_16x16x32_bf16 v[66:69], v[164:167], v[216:219], v[66:69]
	v_mfma_f32_16x16x32_bf16 v[116:119], v[160:163], v[188:191], v[116:119]
	v_mfma_f32_16x16x32_bf16 v[108:111], v[180:183], v[188:191], v[108:111]
	v_mfma_f32_16x16x32_bf16 v[100:103], v[160:163], v[204:207], v[100:103]
	v_mfma_f32_16x16x32_bf16 v[90:93], v[180:183], v[204:207], v[90:93]
	v_mfma_f32_16x16x32_bf16 v[82:85], v[160:163], v[212:215], v[82:85]
	v_mfma_f32_16x16x32_bf16 v[74:77], v[180:183], v[212:215], v[74:77]
	v_mfma_f32_16x16x32_bf16 v[70:73], v[160:163], v[220:223], v[70:73]
	v_mfma_f32_16x16x32_bf16 v[66:69], v[180:183], v[220:223], v[66:69]
	s_setprio 0
	s_barrier
	s_add_i32 s5, s44, s77
	v_lshl_add_u64 v[168:169], s[68:69], 0, v[148:149]
	s_mov_b32 m0, s5
	ds_read_b128 v[184:187], v179 offset:16384
	ds_read_b128 v[188:191], v179 offset:17408
	ds_read_b128 v[192:195], v179 offset:18432
	ds_read_b128 v[204:207], v179 offset:19456
	ds_read_b128 v[208:211], v179 offset:20480
	ds_read_b128 v[212:215], v179 offset:21504
	ds_read_b128 v[216:219], v179 offset:22528
	ds_read_b128 v[220:223], v179 offset:23552
	global_load_lds_dwordx4 v[168:169], off
	s_add_i32 m0, s5, 0x2000
	s_add_u32 s44, s68, 0x40000
	v_lshl_add_u64 v[172:173], s[68:69], 0, v[152:153]
	s_addc_u32 s45, s69, 0
	s_add_i32 s4, s4, s77
	global_load_lds_dwordx4 v[172:173], off
	v_lshl_add_u64 v[176:177], s[44:45], 0, v[148:149]
	s_mov_b32 m0, s4
	v_lshl_add_u64 v[200:201], s[70:71], 0, v[150:151]
	global_load_lds_dwordx4 v[176:177], off
	v_lshl_add_u64 v[176:177], s[44:45], 0, v[152:153]
	s_add_i32 m0, s4, 0x2000
	s_nop 0
	global_load_lds_dwordx4 v[176:177], off
	v_lshl_add_u64 v[176:177], s[70:71], 0, v[98:99]
	s_mov_b32 m0, s94
	s_nop 0
	global_load_lds_dwordx4 v[176:177], off
	s_add_i32 m0, s94, 0x2000
	s_nop 0
	global_load_lds_dwordx4 v[200:201], off
	s_cmp_eq_u32 s93, 12
	s_cbranch_scc1 .Lmy_w9_g1_2
	s_waitcnt vmcnt(8)
	s_branch .Lmy_w9d_g1_2

.Lmy_w9d_g1_2:
	s_waitcnt lgkmcnt(0)
	s_setprio 1
	s_barrier
	v_mfma_f32_16x16x32_bf16 v[62:65], v[132:135], v[184:187], v[62:65]
	v_mfma_f32_16x16x32_bf16 v[58:61], v[140:143], v[184:187], v[58:61]
	v_mfma_f32_16x16x32_bf16 v[54:57], v[132:135], v[192:195], v[54:57]
	v_mfma_f32_16x16x32_bf16 v[46:49], v[140:143], v[192:195], v[46:49]
	v_mfma_f32_16x16x32_bf16 v[38:41], v[132:135], v[208:211], v[38:41]
	v_mfma_f32_16x16x32_bf16 v[30:33], v[140:143], v[208:211], v[30:33]
	v_mfma_f32_16x16x32_bf16 v[22:25], v[132:135], v[216:219], v[22:25]
	v_mfma_f32_16x16x32_bf16 v[14:17], v[140:143], v[216:219], v[14:17]
	v_mfma_f32_16x16x32_bf16 v[62:65], v[136:139], v[188:191], v[62:65]
	v_mfma_f32_16x16x32_bf16 v[58:61], v[144:147], v[188:191], v[58:61]
	v_mfma_f32_16x16x32_bf16 v[54:57], v[136:139], v[204:207], v[54:57]
	v_mfma_f32_16x16x32_bf16 v[46:49], v[144:147], v[204:207], v[46:49]
	v_mfma_f32_16x16x32_bf16 v[38:41], v[136:139], v[212:215], v[38:41]
	v_mfma_f32_16x16x32_bf16 v[30:33], v[144:147], v[212:215], v[30:33]
	v_mfma_f32_16x16x32_bf16 v[22:25], v[136:139], v[220:223], v[22:25]
	v_mfma_f32_16x16x32_bf16 v[14:17], v[144:147], v[220:223], v[14:17]
	s_setprio 0
	s_setprio 1
	v_mfma_f32_16x16x32_bf16 v[50:53], v[156:159], v[184:187], v[50:53]
	v_mfma_f32_16x16x32_bf16 v[42:45], v[164:167], v[184:187], v[42:45]
	v_mfma_f32_16x16x32_bf16 v[34:37], v[156:159], v[192:195], v[34:37]
	v_mfma_f32_16x16x32_bf16 v[26:29], v[164:167], v[192:195], v[26:29]
	v_mfma_f32_16x16x32_bf16 v[18:21], v[156:159], v[208:211], v[18:21]
	v_mfma_f32_16x16x32_bf16 v[10:13], v[164:167], v[208:211], v[10:13]
	v_mfma_f32_16x16x32_bf16 v[6:9], v[156:159], v[216:219], v[6:9]
	v_mfma_f32_16x16x32_bf16 v[2:5], v[164:167], v[216:219], v[2:5]
	v_mfma_f32_16x16x32_bf16 v[50:53], v[160:163], v[188:191], v[50:53]
	v_mfma_f32_16x16x32_bf16 v[42:45], v[180:183], v[188:191], v[42:45]
	v_mfma_f32_16x16x32_bf16 v[34:37], v[160:163], v[204:207], v[34:37]
	v_mfma_f32_16x16x32_bf16 v[26:29], v[180:183], v[204:207], v[26:29]
	v_mfma_f32_16x16x32_bf16 v[18:21], v[160:163], v[212:215], v[18:21]
	v_mfma_f32_16x16x32_bf16 v[10:13], v[180:183], v[212:215], v[10:13]
	v_mfma_f32_16x16x32_bf16 v[6:9], v[160:163], v[220:223], v[6:9]
	v_mfma_f32_16x16x32_bf16 v[2:5], v[180:183], v[220:223], v[2:5]
	s_setprio 0
	s_barrier
	s_add_i32 s4, 0, 0x18000
	s_add_i32 s5, 0, 0x1c000
	v_add_u32_e32 v144, s4, v175
	v_add_u32_e32 v170, s5, v175
	ds_read_b128 v[132:135], v144
	ds_read_b128 v[136:139], v144 offset:1024
	ds_read_b128 v[140:143], v144 offset:2048
	ds_read_b128 v[144:147], v144 offset:3072
	ds_read_b128 v[156:159], v170
	ds_read_b128 v[160:163], v170 offset:1024
	ds_read_b128 v[164:167], v170 offset:2048
	ds_read_b128 v[180:183], v170 offset:3072
	s_add_u32 s44, s70, 0x40000
	s_addc_u32 s45, s71, 0
	v_lshl_add_u64 v[202:203], s[44:45], 0, v[98:99]
	s_add_i32 m0, s94, 0x4000
	ds_read_b128 v[184:187], v179 offset:32768
	ds_read_b128 v[188:191], v179 offset:33792
	ds_read_b128 v[192:195], v179 offset:34816
	ds_read_b128 v[204:207], v179 offset:35840
	ds_read_b128 v[208:211], v179 offset:36864
	ds_read_b128 v[212:215], v179 offset:37888
	ds_read_b128 v[216:219], v179 offset:38912
	ds_read_b128 v[220:223], v179 offset:39936
	global_load_lds_dwordx4 v[202:203], off
	v_lshl_add_u64 v[202:203], s[44:45], 0, v[150:151]
	s_add_i32 m0, s94, 0x6000
	s_nop 0
	global_load_lds_dwordx4 v[202:203], off
	s_waitcnt vmcnt(8)
	s_waitcnt lgkmcnt(0)
	s_setprio 1
	s_barrier
	v_mfma_f32_16x16x32_bf16 v[128:131], v[132:135], v[184:187], v[128:131]
	v_mfma_f32_16x16x32_bf16 v[124:127], v[140:143], v[184:187], v[124:127]
	v_mfma_f32_16x16x32_bf16 v[120:123], v[132:135], v[192:195], v[120:123]
	v_mfma_f32_16x16x32_bf16 v[112:115], v[140:143], v[192:195], v[112:115]
	v_mfma_f32_16x16x32_bf16 v[104:107], v[132:135], v[208:211], v[104:107]
	v_mfma_f32_16x16x32_bf16 v[94:97], v[140:143], v[208:211], v[94:97]
	v_mfma_f32_16x16x32_bf16 v[86:89], v[132:135], v[216:219], v[86:89]
	v_mfma_f32_16x16x32_bf16 v[78:81], v[140:143], v[216:219], v[78:81]
	v_mfma_f32_16x16x32_bf16 v[128:131], v[136:139], v[188:191], v[128:131]
	v_mfma_f32_16x16x32_bf16 v[124:127], v[144:147], v[188:191], v[124:127]
	v_mfma_f32_16x16x32_bf16 v[120:123], v[136:139], v[204:207], v[120:123]
	v_mfma_f32_16x16x32_bf16 v[112:115], v[144:147], v[204:207], v[112:115]
	v_mfma_f32_16x16x32_bf16 v[104:107], v[136:139], v[212:215], v[104:107]
	v_mfma_f32_16x16x32_bf16 v[94:97], v[144:147], v[212:215], v[94:97]
	v_mfma_f32_16x16x32_bf16 v[86:89], v[136:139], v[220:223], v[86:89]
	v_mfma_f32_16x16x32_bf16 v[78:81], v[144:147], v[220:223], v[78:81]
	s_setprio 0
	s_setprio 1
	v_mfma_f32_16x16x32_bf16 v[116:119], v[156:159], v[184:187], v[116:119]
	v_mfma_f32_16x16x32_bf16 v[108:111], v[164:167], v[184:187], v[108:111]
	v_mfma_f32_16x16x32_bf16 v[100:103], v[156:159], v[192:195], v[100:103]
	v_mfma_f32_16x16x32_bf16 v[90:93], v[164:167], v[192:195], v[90:93]
	v_mfma_f32_16x16x32_bf16 v[82:85], v[156:159], v[208:211], v[82:85]
	v_mfma_f32_16x16x32_bf16 v[74:77], v[164:167], v[208:211], v[74:77]
	v_mfma_f32_16x16x32_bf16 v[70:73], v[156:159], v[216:219], v[70:73]
	v_mfma_f32_16x16x32_bf16 v[66:69], v[164:167], v[216:219], v[66:69]
	v_mfma_f32_16x16x32_bf16 v[116:119], v[160:163], v[188:191], v[116:119]
	v_mfma_f32_16x16x32_bf16 v[108:111], v[180:183], v[188:191], v[108:111]
	v_mfma_f32_16x16x32_bf16 v[100:103], v[160:163], v[204:207], v[100:103]
	v_mfma_f32_16x16x32_bf16 v[90:93], v[180:183], v[204:207], v[90:93]
	v_mfma_f32_16x16x32_bf16 v[82:85], v[160:163], v[212:215], v[82:85]
	v_mfma_f32_16x16x32_bf16 v[74:77], v[180:183], v[212:215], v[74:77]
	v_mfma_f32_16x16x32_bf16 v[70:73], v[160:163], v[220:223], v[70:73]
	v_mfma_f32_16x16x32_bf16 v[66:69], v[180:183], v[220:223], v[66:69]
	s_setprio 0
	s_barrier
	s_add_i32 s4, s4, s77
	v_lshl_add_u64 v[168:169], v[168:169], 0, s[42:43]
	s_mov_b32 m0, s4
	ds_read_b128 v[184:187], v179 offset:49152
	ds_read_b128 v[188:191], v179 offset:50176
	ds_read_b128 v[192:195], v179 offset:51200
	ds_read_b128 v[204:207], v179 offset:52224
	ds_read_b128 v[208:211], v179 offset:53248
	ds_read_b128 v[212:215], v179 offset:54272
	ds_read_b128 v[216:219], v179 offset:55296
	ds_read_b128 v[220:223], v179 offset:56320
	global_load_lds_dwordx4 v[168:169], off
	s_add_i32 m0, s4, 0x2000
	s_add_u32 s44, s68, 0x40080
	v_lshl_add_u64 v[168:169], v[172:173], 0, s[42:43]
	s_addc_u32 s45, s69, 0
	s_add_i32 s4, s5, s77
	global_load_lds_dwordx4 v[168:169], off
	v_lshl_add_u64 v[168:169], s[44:45], 0, v[148:149]
	s_mov_b32 m0, s4
	s_nop 0
	global_load_lds_dwordx4 v[168:169], off
	v_lshl_add_u64 v[168:169], s[44:45], 0, v[152:153]
	s_add_i32 m0, s4, 0x2000
	s_nop 0
	global_load_lds_dwordx4 v[168:169], off
	v_lshl_add_u64 v[168:169], v[176:177], 0, s[42:43]
	s_add_i32 m0, s94, 0x8000
	s_nop 0
	global_load_lds_dwordx4 v[168:169], off
	v_lshl_add_u64 v[168:169], v[200:201], 0, s[42:43]
	s_add_i32 m0, s94, 0xa000
	s_nop 0
	global_load_lds_dwordx4 v[168:169], off
	s_cmp_eq_u32 s93, 10
	s_cbranch_scc0 .Lmy_nt_g1
	s_lshl_b32 s101, s89, 14
	v_lshrrev_b32_e32 v249, 6, v0
	v_and_b32_e32 v231, 15, v0
	v_lshl_or_b32 v231, v249, 4, v231
	v_lshl_add_u32 v231, v231, 7, s101
	global_load_dword v197, v231, s[58:59]
	s_waitcnt vmcnt(9)
	s_branch .Lmy_ntd_g1
.Lmy_nt_g1:
	s_waitcnt vmcnt(8)
.Lmy_ntd_g1:
	s_waitcnt lgkmcnt(0)
	s_setprio 1
	s_barrier
	v_mfma_f32_16x16x32_bf16 v[62:65], v[132:135], v[184:187], v[62:65]
	v_mfma_f32_16x16x32_bf16 v[58:61], v[140:143], v[184:187], v[58:61]
	v_mfma_f32_16x16x32_bf16 v[54:57], v[132:135], v[192:195], v[54:57]
	v_mfma_f32_16x16x32_bf16 v[46:49], v[140:143], v[192:195], v[46:49]
	v_mfma_f32_16x16x32_bf16 v[38:41], v[132:135], v[208:211], v[38:41]
	v_mfma_f32_16x16x32_bf16 v[30:33], v[140:143], v[208:211], v[30:33]
	v_mfma_f32_16x16x32_bf16 v[22:25], v[132:135], v[216:219], v[22:25]
	v_mfma_f32_16x16x32_bf16 v[14:17], v[140:143], v[216:219], v[14:17]
	v_mfma_f32_16x16x32_bf16 v[62:65], v[136:139], v[188:191], v[62:65]
	v_mfma_f32_16x16x32_bf16 v[58:61], v[144:147], v[188:191], v[58:61]
	v_mfma_f32_16x16x32_bf16 v[54:57], v[136:139], v[204:207], v[54:57]
	v_mfma_f32_16x16x32_bf16 v[46:49], v[144:147], v[204:207], v[46:49]
	v_mfma_f32_16x16x32_bf16 v[38:41], v[136:139], v[212:215], v[38:41]
	v_mfma_f32_16x16x32_bf16 v[30:33], v[144:147], v[212:215], v[30:33]
	v_mfma_f32_16x16x32_bf16 v[22:25], v[136:139], v[220:223], v[22:25]
	v_mfma_f32_16x16x32_bf16 v[14:17], v[144:147], v[220:223], v[14:17]
	s_setprio 0
	s_setprio 1
	v_mfma_f32_16x16x32_bf16 v[50:53], v[156:159], v[184:187], v[50:53]
	v_mfma_f32_16x16x32_bf16 v[42:45], v[164:167], v[184:187], v[42:45]
	v_mfma_f32_16x16x32_bf16 v[34:37], v[156:159], v[192:195], v[34:37]
	v_mfma_f32_16x16x32_bf16 v[26:29], v[164:167], v[192:195], v[26:29]
	v_mfma_f32_16x16x32_bf16 v[18:21], v[156:159], v[208:211], v[18:21]
	v_mfma_f32_16x16x32_bf16 v[10:13], v[164:167], v[208:211], v[10:13]
	v_mfma_f32_16x16x32_bf16 v[6:9], v[156:159], v[216:219], v[6:9]
	v_mfma_f32_16x16x32_bf16 v[2:5], v[164:167], v[216:219], v[2:5]
	v_mfma_f32_16x16x32_bf16 v[50:53], v[160:163], v[188:191], v[50:53]
	v_mfma_f32_16x16x32_bf16 v[42:45], v[180:183], v[188:191], v[42:45]
	v_mfma_f32_16x16x32_bf16 v[34:37], v[160:163], v[204:207], v[34:37]
	v_mfma_f32_16x16x32_bf16 v[26:29], v[180:183], v[204:207], v[26:29]
	v_mfma_f32_16x16x32_bf16 v[18:21], v[160:163], v[212:215], v[18:21]
	v_mfma_f32_16x16x32_bf16 v[10:13], v[180:183], v[212:215], v[10:13]
	v_mfma_f32_16x16x32_bf16 v[6:9], v[160:163], v[220:223], v[6:9]
	v_mfma_f32_16x16x32_bf16 v[2:5], v[180:183], v[220:223], v[2:5]
	s_setprio 0
	s_barrier
	s_mov_b32 s100, 0
	s_add_i32 s93, s93, 2
	s_add_u32 s0, s0, 0x100
	s_addc_u32 s1, s1, 0
	s_add_u32 s91, s91, 0x100
	s_addc_u32 s92, s92, 0
	s_cmp_gt_u32 s93, 13
	s_cbranch_scc0 .LBB0_322
	s_mov_b32 s100, 1
	s_and_b64 vcc, exec, s[14:15]
	s_cbranch_vccz .LBB0_325
	s_barrier

.LBB0_1011:
	s_add_u32 s4, s40, 0xfffc0080
	s_addc_u32 s5, s41, -1
	s_add_i32 s6, 0, 0x10000
	s_cmp_eq_u32 s92, 12
	s_cselect_b32 s69, s21, s5
	s_cselect_b32 s68, s88, s4
	s_cselect_b32 s57, s15, s91
	s_cselect_b32 s56, s89, s90
	s_add_i32 s7, 0, 0x14000
	v_add_u32_e32 v144, s6, v189
	v_add_u32_e32 v160, s7, v189
	ds_read_b128 v[132:135], v144
	ds_read_b128 v[136:139], v144 offset:1024
	ds_read_b128 v[140:143], v144 offset:2048
	ds_read_b128 v[144:147], v144 offset:3072
	ds_read_b128 v[156:159], v160
	ds_read_b128 v[162:165], v160 offset:1024
	ds_read_b128 v[192:195], v160 offset:2048
	ds_read_b128 v[200:203], v160 offset:3072
	s_add_i32 s44, s70, 0
	v_lshl_add_u64 v[166:167], s[40:41], 0, v[98:99]
	s_add_i32 m0, s44, 0xc000
	ds_read_b128 v[204:207], v191
	ds_read_b128 v[208:211], v191 offset:1024
	ds_read_b128 v[212:215], v191 offset:2048
	ds_read_b128 v[216:219], v191 offset:3072
	ds_read_b128 v[220:223], v191 offset:4096
	ds_read_b128 v[224:227], v191 offset:5120
	ds_read_b128 v[238:241], v191 offset:6144
	ds_read_b128 v[242:245], v191 offset:7168
	global_load_lds_dwordx4 v[166:167], off
	v_lshl_add_u64 v[166:167], s[40:41], 0, v[150:151]
	s_add_i32 m0, s44, 0xe000
	s_nop 0
	global_load_lds_dwordx4 v[166:167], off
	s_cmp_eq_u32 s92, 12
	s_cbranch_scc1 .Lmy_w9_g3_1
	s_waitcnt vmcnt(8)
	s_branch .Lmy_w9d_g3_1

.Lmy_w9d_g3_1:
	s_waitcnt lgkmcnt(0)
	s_setprio 1
	s_barrier
	v_mfma_f32_16x16x32_bf16 v[128:131], v[132:135], v[204:207], v[128:131]
	v_mfma_f32_16x16x32_bf16 v[124:127], v[140:143], v[204:207], v[124:127]
	v_mfma_f32_16x16x32_bf16 v[112:115], v[132:135], v[212:215], v[112:115]
	v_mfma_f32_16x16x32_bf16 v[108:111], v[140:143], v[212:215], v[108:111]
	v_mfma_f32_16x16x32_bf16 v[94:97], v[132:135], v[220:223], v[94:97]
	v_mfma_f32_16x16x32_bf16 v[90:93], v[140:143], v[220:223], v[90:93]
	v_mfma_f32_16x16x32_bf16 v[78:81], v[132:135], v[238:241], v[78:81]
	v_mfma_f32_16x16x32_bf16 v[74:77], v[140:143], v[238:241], v[74:77]
	v_mfma_f32_16x16x32_bf16 v[128:131], v[136:139], v[208:211], v[128:131]
	v_mfma_f32_16x16x32_bf16 v[124:127], v[144:147], v[208:211], v[124:127]
	v_mfma_f32_16x16x32_bf16 v[112:115], v[136:139], v[216:219], v[112:115]
	v_mfma_f32_16x16x32_bf16 v[108:111], v[144:147], v[216:219], v[108:111]
	v_mfma_f32_16x16x32_bf16 v[94:97], v[136:139], v[224:227], v[94:97]
	v_mfma_f32_16x16x32_bf16 v[90:93], v[144:147], v[224:227], v[90:93]
	v_mfma_f32_16x16x32_bf16 v[78:81], v[136:139], v[242:245], v[78:81]
	v_mfma_f32_16x16x32_bf16 v[74:77], v[144:147], v[242:245], v[74:77]
	s_setprio 0
	s_setprio 1
	v_mfma_f32_16x16x32_bf16 v[120:123], v[156:159], v[204:207], v[120:123]
	v_mfma_f32_16x16x32_bf16 v[116:119], v[192:195], v[204:207], v[116:119]
	v_mfma_f32_16x16x32_bf16 v[104:107], v[156:159], v[212:215], v[104:107]
	v_mfma_f32_16x16x32_bf16 v[100:103], v[192:195], v[212:215], v[100:103]
	v_mfma_f32_16x16x32_bf16 v[86:89], v[156:159], v[220:223], v[86:89]
	v_mfma_f32_16x16x32_bf16 v[82:85], v[192:195], v[220:223], v[82:85]
	v_mfma_f32_16x16x32_bf16 v[70:73], v[156:159], v[238:241], v[70:73]
	v_mfma_f32_16x16x32_bf16 v[66:69], v[192:195], v[238:241], v[66:69]
	v_mfma_f32_16x16x32_bf16 v[120:123], v[162:165], v[208:211], v[120:123]
	v_mfma_f32_16x16x32_bf16 v[116:119], v[200:203], v[208:211], v[116:119]
	v_mfma_f32_16x16x32_bf16 v[104:107], v[162:165], v[216:219], v[104:107]
	v_mfma_f32_16x16x32_bf16 v[100:103], v[200:203], v[216:219], v[100:103]
	v_mfma_f32_16x16x32_bf16 v[86:89], v[162:165], v[224:227], v[86:89]
	v_mfma_f32_16x16x32_bf16 v[82:85], v[200:203], v[224:227], v[82:85]
	v_mfma_f32_16x16x32_bf16 v[70:73], v[162:165], v[242:245], v[70:73]
	v_mfma_f32_16x16x32_bf16 v[66:69], v[200:203], v[242:245], v[66:69]
	s_setprio 0
	s_barrier
	s_add_i32 s4, s6, s70
	v_lshl_add_u64 v[166:167], s[56:57], 0, v[148:149]
	s_mov_b32 m0, s4
	ds_read_b128 v[204:207], v191 offset:16384
	ds_read_b128 v[208:211], v191 offset:17408
	ds_read_b128 v[212:215], v191 offset:18432
	ds_read_b128 v[216:219], v191 offset:19456
	ds_read_b128 v[220:223], v191 offset:20480
	ds_read_b128 v[224:227], v191 offset:21504
	ds_read_b128 v[238:241], v191 offset:22528
	ds_read_b128 v[242:245], v191 offset:23552
	global_load_lds_dwordx4 v[166:167], off
	s_add_i32 m0, s4, 0x2000
	s_add_u32 s4, s56, 0x40000
	v_lshl_add_u64 v[170:171], s[56:57], 0, v[152:153]
	s_addc_u32 s5, s57, 0
	s_add_i32 s6, s7, s70
	global_load_lds_dwordx4 v[170:171], off
	v_lshl_add_u64 v[176:177], s[4:5], 0, v[148:149]
	s_mov_b32 m0, s6
	v_lshl_add_u64 v[180:181], s[68:69], 0, v[150:151]
	global_load_lds_dwordx4 v[176:177], off
	v_lshl_add_u64 v[176:177], s[4:5], 0, v[152:153]
	s_add_i32 m0, s6, 0x2000
	s_nop 0
	global_load_lds_dwordx4 v[176:177], off
	v_lshl_add_u64 v[176:177], s[68:69], 0, v[98:99]
	s_mov_b32 m0, s44
	s_nop 0
	global_load_lds_dwordx4 v[176:177], off
	s_add_i32 m0, s44, 0x2000
	s_nop 0
	global_load_lds_dwordx4 v[180:181], off
	s_cmp_eq_u32 s92, 12
	s_cbranch_scc1 .Lmy_w9_g3_2
	s_waitcnt vmcnt(8)
	s_branch .Lmy_w9d_g3_2

.Lmy_w9d_g3_2:
	s_waitcnt lgkmcnt(0)
	s_setprio 1
	s_barrier
	v_mfma_f32_16x16x32_bf16 v[62:65], v[132:135], v[204:207], v[62:65]
	v_mfma_f32_16x16x32_bf16 v[58:61], v[140:143], v[204:207], v[58:61]
	v_mfma_f32_16x16x32_bf16 v[46:49], v[132:135], v[212:215], v[46:49]
	v_mfma_f32_16x16x32_bf16 v[42:45], v[140:143], v[212:215], v[42:45]
	v_mfma_f32_16x16x32_bf16 v[30:33], v[132:135], v[220:223], v[30:33]
	v_mfma_f32_16x16x32_bf16 v[26:29], v[140:143], v[220:223], v[26:29]
	v_mfma_f32_16x16x32_bf16 v[14:17], v[132:135], v[238:241], v[14:17]
	v_mfma_f32_16x16x32_bf16 v[10:13], v[140:143], v[238:241], v[10:13]
	v_mfma_f32_16x16x32_bf16 v[62:65], v[136:139], v[208:211], v[62:65]
	v_mfma_f32_16x16x32_bf16 v[58:61], v[144:147], v[208:211], v[58:61]
	v_mfma_f32_16x16x32_bf16 v[46:49], v[136:139], v[216:219], v[46:49]
	v_mfma_f32_16x16x32_bf16 v[42:45], v[144:147], v[216:219], v[42:45]
	v_mfma_f32_16x16x32_bf16 v[30:33], v[136:139], v[224:227], v[30:33]
	v_mfma_f32_16x16x32_bf16 v[26:29], v[144:147], v[224:227], v[26:29]
	v_mfma_f32_16x16x32_bf16 v[14:17], v[136:139], v[242:245], v[14:17]
	v_mfma_f32_16x16x32_bf16 v[10:13], v[144:147], v[242:245], v[10:13]
	s_setprio 0
	s_setprio 1
	v_mfma_f32_16x16x32_bf16 v[54:57], v[156:159], v[204:207], v[54:57]
	v_mfma_f32_16x16x32_bf16 v[50:53], v[192:195], v[204:207], v[50:53]
	v_mfma_f32_16x16x32_bf16 v[38:41], v[156:159], v[212:215], v[38:41]
	v_mfma_f32_16x16x32_bf16 v[34:37], v[192:195], v[212:215], v[34:37]
	v_mfma_f32_16x16x32_bf16 v[22:25], v[156:159], v[220:223], v[22:25]
	v_mfma_f32_16x16x32_bf16 v[18:21], v[192:195], v[220:223], v[18:21]
	v_mfma_f32_16x16x32_bf16 v[6:9], v[156:159], v[238:241], v[6:9]
	v_mfma_f32_16x16x32_bf16 v[2:5], v[192:195], v[238:241], v[2:5]
	v_mfma_f32_16x16x32_bf16 v[54:57], v[162:165], v[208:211], v[54:57]
	v_mfma_f32_16x16x32_bf16 v[50:53], v[200:203], v[208:211], v[50:53]
	v_mfma_f32_16x16x32_bf16 v[38:41], v[162:165], v[216:219], v[38:41]
	v_mfma_f32_16x16x32_bf16 v[34:37], v[200:203], v[216:219], v[34:37]
	v_mfma_f32_16x16x32_bf16 v[22:25], v[162:165], v[224:227], v[22:25]
	v_mfma_f32_16x16x32_bf16 v[18:21], v[200:203], v[224:227], v[18:21]
	v_mfma_f32_16x16x32_bf16 v[6:9], v[162:165], v[242:245], v[6:9]
	v_mfma_f32_16x16x32_bf16 v[2:5], v[200:203], v[242:245], v[2:5]
	s_setprio 0
	s_barrier
	s_add_i32 s6, 0, 0x18000
	s_add_i32 s7, 0, 0x1c000
	v_add_u32_e32 v144, s6, v189
	v_add_u32_e32 v160, s7, v189
	ds_read_b128 v[132:135], v144
	ds_read_b128 v[136:139], v144 offset:1024
	ds_read_b128 v[140:143], v144 offset:2048
	ds_read_b128 v[144:147], v144 offset:3072
	ds_read_b128 v[156:159], v160
	ds_read_b128 v[162:165], v160 offset:1024
	ds_read_b128 v[192:195], v160 offset:2048
	ds_read_b128 v[200:203], v160 offset:3072
	s_add_u32 s4, s68, 0x40000
	s_addc_u32 s5, s69, 0
	v_lshl_add_u64 v[246:247], s[4:5], 0, v[98:99]
	s_add_i32 m0, s44, 0x4000
	ds_read_b128 v[204:207], v191 offset:32768
	ds_read_b128 v[208:211], v191 offset:33792
	ds_read_b128 v[212:215], v191 offset:34816
	ds_read_b128 v[216:219], v191 offset:35840
	ds_read_b128 v[220:223], v191 offset:36864
	ds_read_b128 v[224:227], v191 offset:37888
	ds_read_b128 v[238:241], v191 offset:38912
	ds_read_b128 v[242:245], v191 offset:39936
	global_load_lds_dwordx4 v[246:247], off
	v_lshl_add_u64 v[246:247], s[4:5], 0, v[150:151]
	s_add_i32 m0, s44, 0x6000
	s_nop 0
	global_load_lds_dwordx4 v[246:247], off
	s_waitcnt vmcnt(8)
	s_waitcnt lgkmcnt(0)
	s_setprio 1
	s_barrier
	v_mfma_f32_16x16x32_bf16 v[128:131], v[132:135], v[204:207], v[128:131]
	v_mfma_f32_16x16x32_bf16 v[124:127], v[140:143], v[204:207], v[124:127]
	v_mfma_f32_16x16x32_bf16 v[112:115], v[132:135], v[212:215], v[112:115]
	v_mfma_f32_16x16x32_bf16 v[108:111], v[140:143], v[212:215], v[108:111]
	v_mfma_f32_16x16x32_bf16 v[94:97], v[132:135], v[220:223], v[94:97]
	v_mfma_f32_16x16x32_bf16 v[90:93], v[140:143], v[220:223], v[90:93]
	v_mfma_f32_16x16x32_bf16 v[78:81], v[132:135], v[238:241], v[78:81]
	v_mfma_f32_16x16x32_bf16 v[74:77], v[140:143], v[238:241], v[74:77]
	v_mfma_f32_16x16x32_bf16 v[128:131], v[136:139], v[208:211], v[128:131]
	v_mfma_f32_16x16x32_bf16 v[124:127], v[144:147], v[208:211], v[124:127]
	v_mfma_f32_16x16x32_bf16 v[112:115], v[136:139], v[216:219], v[112:115]
	v_mfma_f32_16x16x32_bf16 v[108:111], v[144:147], v[216:219], v[108:111]
	v_mfma_f32_16x16x32_bf16 v[94:97], v[136:139], v[224:227], v[94:97]
	v_mfma_f32_16x16x32_bf16 v[90:93], v[144:147], v[224:227], v[90:93]
	v_mfma_f32_16x16x32_bf16 v[78:81], v[136:139], v[242:245], v[78:81]
	v_mfma_f32_16x16x32_bf16 v[74:77], v[144:147], v[242:245], v[74:77]
	s_setprio 0
	s_setprio 1
	v_mfma_f32_16x16x32_bf16 v[120:123], v[156:159], v[204:207], v[120:123]
	v_mfma_f32_16x16x32_bf16 v[116:119], v[192:195], v[204:207], v[116:119]
	v_mfma_f32_16x16x32_bf16 v[104:107], v[156:159], v[212:215], v[104:107]
	v_mfma_f32_16x16x32_bf16 v[100:103], v[192:195], v[212:215], v[100:103]
	v_mfma_f32_16x16x32_bf16 v[86:89], v[156:159], v[220:223], v[86:89]
	v_mfma_f32_16x16x32_bf16 v[82:85], v[192:195], v[220:223], v[82:85]
	v_mfma_f32_16x16x32_bf16 v[70:73], v[156:159], v[238:241], v[70:73]
	v_mfma_f32_16x16x32_bf16 v[66:69], v[192:195], v[238:241], v[66:69]
	v_mfma_f32_16x16x32_bf16 v[120:123], v[162:165], v[208:211], v[120:123]
	v_mfma_f32_16x16x32_bf16 v[116:119], v[200:203], v[208:211], v[116:119]
	v_mfma_f32_16x16x32_bf16 v[104:107], v[162:165], v[216:219], v[104:107]
	v_mfma_f32_16x16x32_bf16 v[100:103], v[200:203], v[216:219], v[100:103]
	v_mfma_f32_16x16x32_bf16 v[86:89], v[162:165], v[224:227], v[86:89]
	v_mfma_f32_16x16x32_bf16 v[82:85], v[200:203], v[224:227], v[82:85]
	v_mfma_f32_16x16x32_bf16 v[70:73], v[162:165], v[242:245], v[70:73]
	v_mfma_f32_16x16x32_bf16 v[66:69], v[200:203], v[242:245], v[66:69]
	s_setprio 0
	s_barrier
	s_add_i32 s4, s6, s70
	v_lshl_add_u64 v[166:167], v[166:167], 0, s[42:43]
	s_mov_b32 m0, s4
	ds_read_b128 v[204:207], v191 offset:49152
	ds_read_b128 v[208:211], v191 offset:50176
	ds_read_b128 v[212:215], v191 offset:51200
	ds_read_b128 v[216:219], v191 offset:52224
	ds_read_b128 v[220:223], v191 offset:53248
	ds_read_b128 v[224:227], v191 offset:54272
	ds_read_b128 v[238:241], v191 offset:55296
	ds_read_b128 v[242:245], v191 offset:56320
	global_load_lds_dwordx4 v[166:167], off
	s_add_i32 m0, s4, 0x2000
	s_add_u32 s4, s56, 0x40080
	v_lshl_add_u64 v[166:167], v[170:171], 0, s[42:43]
	s_addc_u32 s5, s57, 0
	s_add_i32 s6, s7, s70
	global_load_lds_dwordx4 v[166:167], off
	v_lshl_add_u64 v[166:167], s[4:5], 0, v[148:149]
	s_mov_b32 m0, s6
	s_nop 0
	global_load_lds_dwordx4 v[166:167], off
	v_lshl_add_u64 v[166:167], s[4:5], 0, v[152:153]
	s_add_i32 m0, s6, 0x2000
	s_nop 0
	global_load_lds_dwordx4 v[166:167], off
	v_lshl_add_u64 v[166:167], v[176:177], 0, s[42:43]
	s_add_i32 m0, s44, 0x8000
	s_nop 0
	global_load_lds_dwordx4 v[166:167], off
	v_lshl_add_u64 v[166:167], v[180:181], 0, s[42:43]
	s_add_i32 m0, s44, 0xa000
	s_nop 0
	global_load_lds_dwordx4 v[166:167], off
	s_cmp_eq_u32 s92, 10
	s_cbranch_scc0 .Lmy_nt_g3
	s_lshl_b32 s101, s77, 14
	v_lshrrev_b32_e32 v249, 6, v0
	v_and_b32_e32 v231, 15, v0
	v_lshl_or_b32 v231, v249, 4, v231
	v_lshl_add_u32 v231, v231, 7, s101
	global_load_dword v197, v231, s[58:59]
	s_waitcnt vmcnt(9)
	s_branch .Lmy_ntd_g3

.Lmy_ntd_g3:
	s_waitcnt lgkmcnt(0)
	s_setprio 1
	s_barrier
	v_mfma_f32_16x16x32_bf16 v[62:65], v[132:135], v[204:207], v[62:65]
	v_mfma_f32_16x16x32_bf16 v[58:61], v[140:143], v[204:207], v[58:61]
	v_mfma_f32_16x16x32_bf16 v[46:49], v[132:135], v[212:215], v[46:49]
	v_mfma_f32_16x16x32_bf16 v[42:45], v[140:143], v[212:215], v[42:45]
	v_mfma_f32_16x16x32_bf16 v[30:33], v[132:135], v[220:223], v[30:33]
	v_mfma_f32_16x16x32_bf16 v[26:29], v[140:143], v[220:223], v[26:29]
	v_mfma_f32_16x16x32_bf16 v[14:17], v[132:135], v[238:241], v[14:17]
	v_mfma_f32_16x16x32_bf16 v[10:13], v[140:143], v[238:241], v[10:13]
	v_mfma_f32_16x16x32_bf16 v[62:65], v[136:139], v[208:211], v[62:65]
	v_mfma_f32_16x16x32_bf16 v[58:61], v[144:147], v[208:211], v[58:61]
	v_mfma_f32_16x16x32_bf16 v[46:49], v[136:139], v[216:219], v[46:49]
	v_mfma_f32_16x16x32_bf16 v[42:45], v[144:147], v[216:219], v[42:45]
	v_mfma_f32_16x16x32_bf16 v[30:33], v[136:139], v[224:227], v[30:33]
	v_mfma_f32_16x16x32_bf16 v[26:29], v[144:147], v[224:227], v[26:29]
	v_mfma_f32_16x16x32_bf16 v[14:17], v[136:139], v[242:245], v[14:17]
	v_mfma_f32_16x16x32_bf16 v[10:13], v[144:147], v[242:245], v[10:13]
	s_setprio 0
	s_setprio 1
	v_mfma_f32_16x16x32_bf16 v[54:57], v[156:159], v[204:207], v[54:57]
	v_mfma_f32_16x16x32_bf16 v[50:53], v[192:195], v[204:207], v[50:53]
	v_mfma_f32_16x16x32_bf16 v[38:41], v[156:159], v[212:215], v[38:41]
	v_mfma_f32_16x16x32_bf16 v[34:37], v[192:195], v[212:215], v[34:37]
	v_mfma_f32_16x16x32_bf16 v[22:25], v[156:159], v[220:223], v[22:25]
	v_mfma_f32_16x16x32_bf16 v[18:21], v[192:195], v[220:223], v[18:21]
	v_mfma_f32_16x16x32_bf16 v[6:9], v[156:159], v[238:241], v[6:9]
	v_mfma_f32_16x16x32_bf16 v[2:5], v[192:195], v[238:241], v[2:5]
	v_mfma_f32_16x16x32_bf16 v[54:57], v[162:165], v[208:211], v[54:57]
	v_mfma_f32_16x16x32_bf16 v[50:53], v[200:203], v[208:211], v[50:53]
	v_mfma_f32_16x16x32_bf16 v[38:41], v[162:165], v[216:219], v[38:41]
	v_mfma_f32_16x16x32_bf16 v[34:37], v[200:203], v[216:219], v[34:37]
	v_mfma_f32_16x16x32_bf16 v[22:25], v[162:165], v[224:227], v[22:25]
	v_mfma_f32_16x16x32_bf16 v[18:21], v[200:203], v[224:227], v[18:21]
	v_mfma_f32_16x16x32_bf16 v[6:9], v[162:165], v[242:245], v[6:9]
	v_mfma_f32_16x16x32_bf16 v[2:5], v[200:203], v[242:245], v[2:5]
	s_setprio 0
	s_barrier
	s_mov_b32 s100, 0
	s_add_i32 s92, s92, 2
	s_add_u32 s40, s40, 0x100
	s_addc_u32 s41, s41, 0
	s_add_u32 s90, s90, 0x100
	s_addc_u32 s91, s91, 0
	s_cmp_gt_u32 s92, 13
	s_cbranch_scc0 .LBB0_1011
	s_mov_b32 s100, 1
	s_and_b64 vcc, exec, s[0:1]
	s_cbranch_vccz .LBB0_1014
	s_barrier
